# speedup vs baseline: 1.0147x; 1.0031x over previous
; DI void mix_gmlp(CP& p, int l, int ci, LAS unsigned char* lds) {
;     ...
;       for (int ct = 0; ct < 8; ++ct) {
;         f32x4 acc = {0.f, 0.f, 0.f, 0.f};
; #pragma unroll
;         for (int ks = 0; ks < 4; ++ks) {
;           if (ks < nks) {
;             bf16x8 vf;
; #pragma unroll
;             for (int e = 0; e < 8; ++e) vf[e] = (short)vn[(32 * ks + 8 * fq + e) * VSTR + g * 128 + ct * 16 + fr];
;             acc = __builtin_amdgcn_mfma_f32_16x16x32_bf16(vf, wf[ks], acc, 0, 0, 0);
;           }
;         }
.LBB0_162:
	global_load_dwordx2 v[48:49], v[30:31], off
	global_load_dwordx2 v[50:51], v[30:31], off offset:-2048
	v_add_u32_e32 v34, s4, v32
	ds_read_u16 v16, v34 offset:2056
	ds_read_u16 v17, v34 offset:3084
	ds_read_u16 v18, v34 offset:4112
	ds_read_u16 v19, v34 offset:6168
	ds_read_u16 v35, v34 offset:7196
	ds_read_u16 v36, v34 offset:5140
	ds_read_u16 v37, v34
	ds_read_u16 v38, v34 offset:1028
	s_waitcnt lgkmcnt(6)
	v_perm_b32 v17, v17, v16, s99
	s_waitcnt lgkmcnt(3)
	v_perm_b32 v19, v35, v19, s99
	s_waitcnt lgkmcnt(2)
	v_perm_b32 v18, v36, v18, s99
	s_waitcnt lgkmcnt(0)
	v_perm_b32 v16, v38, v37, s99
	ds_read_u16 v35, v34 offset:34952
	ds_read_u16 v36, v34 offset:35980
	ds_read_u16 v37, v34 offset:37008
	ds_read_u16 v38, v34 offset:39064
	ds_read_u16 v39, v34 offset:40092
	ds_read_u16 v40, v34 offset:38036
	ds_read_u16 v41, v34 offset:32896
	ds_read_u16 v42, v34 offset:33924
	s_waitcnt vmcnt(6)
	v_mfma_f32_16x16x32_bf16 v[16:19], v[16:19], v[0:3], 0
	s_waitcnt lgkmcnt(3)
	v_perm_b32 v39, v39, v38, s99
	s_waitcnt lgkmcnt(2)
	v_perm_b32 v38, v40, v37, s99
	v_perm_b32 v37, v36, v35, s99
	s_waitcnt lgkmcnt(0)
	v_perm_b32 v36, v42, v41, s99
	s_waitcnt vmcnt(5)
	s_nop 0
	v_mfma_f32_16x16x32_bf16 v[16:19], v[36:39], v[4:7], v[16:19]
	s_and_saveexec_b64 s[16:17], s[8:9]
	s_cbranch_execnz .LBB0_165
	s_or_b64 exec, exec, s[16:17]
	s_and_saveexec_b64 s[16:17], s[8:9]
	s_cbranch_execnz .LBB0_166

; DI unsigned pk2(float lo, float hi) { unsigned r; asm("v_cvt_pk_bf16_f32 %0, %1, %2" : "=v"(r) : "v"(lo), "v"(hi)); return r; }
; DI float bflo(unsigned u) { return __uint_as_float(u << 16); }
; DI float bfhi(unsigned u) { return __uint_as_float(u & 0xffff0000u); }
; DI float silu(float x) { return x * __builtin_amdgcn_rcpf(1.f + __expf(-x)); }
; DI void mix_gmlp(CP& p, int l, int ci, LAS unsigned char* lds) {
;     ...
; #pragma unroll
;         for (int ks = 0; ks < 4; ++ks) {
;           if (ks < nks) {
;             bf16x8 vf;
; #pragma unroll
;             for (int e = 0; e < 8; ++e) vf[e] = (short)vn[(32 * ks + 8 * fq + e) * VSTR + g * 128 + ct * 16 + fr];
;             acc = __builtin_amdgcn_mfma_f32_16x16x32_bf16(vf, wf[ks], acc, 0, 0, 0);
;           }
;         }
;         const int c0 = g * 128 + ct * 16 + 4 * fq;
;         if (i < nvalid) {
;           const u16* pr = proj + (size_t)(r0 + i) * NPROJ;
;           const u32x2 au = *(const u32x2*)(pr + C_AU + c0), ag = *(const u32x2*)(pr + C_AG + c0);
;           const float o0 = bflo(au.x) * (acc.x + bsv) * silu(bflo(ag.x)), o1 = bfhi(au.x) * (acc.y + bsv) * silu(bfhi(ag.x));
;           const float o2 = bflo(au.y) * (acc.z + bsv) * silu(bflo(ag.y)), o3 = bfhi(au.y) * (acc.w + bsv) * silu(bfhi(ag.y));
;           u32x2 o; o.x = pk2(o0, o1); o.y = pk2(o2, o3);
;           *(u32x2*)(y + (size_t)(r0 + i) * DM + c0) = o;
.LBB0_165:
	v_add_u32_e32 v35, 0x10100, v34
	v_add_u32_e32 v36, 0x10504, v34
	v_add_u32_e32 v37, 0x10908, v34
	v_add_u32_e32 v38, 0x10d0c, v34
	v_add_u32_e32 v39, 0x11110, v34
	v_add_u32_e32 v40, 0x11514, v34
	v_add_u32_e32 v41, 0x11918, v34
	v_add_u32_e32 v42, 0x11d1c, v34
	ds_read_u16 v37, v37
	ds_read_u16 v43, v38
	ds_read_u16 v38, v39
	ds_read_u16 v39, v41
	ds_read_u16 v41, v42
	ds_read_u16 v40, v40
	ds_read_u16 v35, v35
	ds_read_u16 v36, v36
	s_waitcnt lgkmcnt(6)
	v_perm_b32 v37, v43, v37, s99
	s_waitcnt lgkmcnt(3)
	v_perm_b32 v39, v41, v39, s99
	s_waitcnt lgkmcnt(2)
	v_perm_b32 v38, v40, v38, s99
	s_waitcnt lgkmcnt(0)
	v_perm_b32 v36, v36, v35, s99
	s_waitcnt vmcnt(4)
	s_nop 0
	v_mfma_f32_16x16x32_bf16 v[16:19], v[36:39], v[8:11], v[16:19]
	s_or_b64 exec, exec, s[16:17]
	s_and_saveexec_b64 s[16:17], s[8:9]
	s_cbranch_execz .LBB0_164
.LBB0_166:
	v_add_u32_e32 v35, 0x18180, v34
	v_add_u32_e32 v36, 0x18584, v34
	v_add_u32_e32 v37, 0x18988, v34
	v_add_u32_e32 v38, 0x18d8c, v34
	v_add_u32_e32 v39, 0x19190, v34
	v_add_u32_e32 v40, 0x19594, v34
	v_add_u32_e32 v41, 0x19998, v34
	v_add_u32_e32 v34, 0x19d9c, v34
	ds_read_u16 v42, v37
	ds_read_u16 v38, v38
	ds_read_u16 v39, v39
	ds_read_u16 v37, v41
	ds_read_u16 v34, v34
	ds_read_u16 v40, v40
	ds_read_u16 v41, v35
	ds_read_u16 v43, v36
	s_waitcnt lgkmcnt(6)
	v_perm_b32 v35, v38, v42, s99
	s_waitcnt lgkmcnt(3)
	v_perm_b32 v37, v34, v37, s99
	s_waitcnt lgkmcnt(2)
	v_perm_b32 v36, v40, v39, s99
	s_waitcnt lgkmcnt(0)
	v_perm_b32 v34, v43, v41, s99
	s_waitcnt vmcnt(3)
	s_nop 0
	v_mfma_f32_16x16x32_bf16 v[16:19], v[34:37], v[12:15], v[16:19]
	s_or_b64 exec, exec, s[16:17]
	s_and_saveexec_b64 s[16:17], s[10:11]
	s_cbranch_execz .LBB0_161
.LBB0_167:
	s_waitcnt vmcnt(2)
	s_nop 1
	v_add_f32_e32 v38, v33, v17
	v_add_f32_e32 v40, v33, v19
	v_add_f32_e32 v16, v33, v16
	v_add_f32_e32 v18, v33, v18
	s_waitcnt vmcnt(1)
	v_mov_b32_e32 v34, v48
	v_mov_b32_e32 v35, v49
	v_lshlrev_b32_e32 v43, 16, v34
	v_and_b32_e32 v45, 0xffff0000, v34
	v_lshlrev_b32_e32 v47, 16, v35
	v_and_b32_e32 v35, 0xffff0000, v35
	v_mul_f32_e32 v17, 0xbfb8aa3b, v43
	v_mul_f32_e32 v19, 0xbfb8aa3b, v45
	s_waitcnt vmcnt(0)
	v_mov_b32_e32 v36, v50
	v_mov_b32_e32 v37, v51
	v_lshlrev_b32_e32 v42, 16, v36
	v_and_b32_e32 v44, 0xffff0000, v36
	v_lshlrev_b32_e32 v46, 16, v37
	v_and_b32_e32 v34, 0xffff0000, v37
	v_mul_f32_e32 v36, 0xbfb8aa3b, v47
	v_mul_f32_e32 v37, 0xbfb8aa3b, v35
	v_exp_f32_e32 v17, v17
	v_exp_f32_e32 v19, v19
	v_exp_f32_e32 v36, v36
	v_exp_f32_e32 v37, v37
	v_add_f32_e32 v17, 1.0, v17
	v_add_f32_e32 v19, 1.0, v19
	v_add_f32_e32 v36, 1.0, v36
	v_add_f32_e32 v37, 1.0, v37
	v_rcp_f32_e32 v17, v17
	v_rcp_f32_e32 v39, v19
	v_rcp_f32_e32 v19, v36
	v_rcp_f32_e32 v41, v37
	v_pk_mul_f32 v[16:17], v[16:17], v[42:43]
	v_pk_mul_f32 v[36:37], v[38:39], v[44:45]
	v_pk_mul_f32 v[18:19], v[18:19], v[46:47]
	v_pk_mul_f32 v[34:35], v[40:41], v[34:35]
	v_mul_f32_e32 v16, v16, v17
	v_mul_f32_e32 v17, v36, v37
	v_mul_f32_e32 v18, v18, v19
	v_mul_f32_e32 v19, v34, v35
	v_cvt_pk_bf16_f32 v16, v16, v17
	v_cvt_pk_bf16_f32 v17, v18, v19
	global_store_dwordx2 v[28:29], v[16:17], off
	s_branch .LBB0_161

; DI void mix_gmlp(CP& p, int l, int ci, LAS unsigned char* lds) {
;     ...
;       for (int ct = 0; ct < 8; ++ct) {
;         f32x4 acc = {0.f, 0.f, 0.f, 0.f};
; #pragma unroll
;         for (int ks = 0; ks < 4; ++ks) {
;           if (ks < nks) {
;             bf16x8 vf;
; #pragma unroll
;             for (int e = 0; e < 8; ++e) vf[e] = (short)vn[(32 * ks + 8 * fq + e) * VSTR + g * 128 + ct * 16 + fr];
;             acc = __builtin_amdgcn_mfma_f32_16x16x32_bf16(vf, wf[ks], acc, 0, 0, 0);
;           }
;         }
.LBB0_170:
	global_load_dwordx2 v[48:49], v[28:29], off
	global_load_dwordx2 v[50:51], v[28:29], off offset:-2048
	v_add_u32_e32 v34, s4, v32
	ds_read_u16 v16, v34 offset:2312
	ds_read_u16 v17, v34 offset:3340
	ds_read_u16 v18, v34 offset:4368
	ds_read_u16 v19, v34 offset:6424
	ds_read_u16 v35, v34 offset:7452
	ds_read_u16 v36, v34 offset:5396
	ds_read_u16 v37, v34 offset:256
	ds_read_u16 v38, v34 offset:1284
	s_waitcnt lgkmcnt(6)
	v_perm_b32 v17, v17, v16, s99
	s_waitcnt lgkmcnt(3)
	v_perm_b32 v19, v35, v19, s99
	s_waitcnt lgkmcnt(2)
	v_perm_b32 v18, v36, v18, s99
	s_waitcnt lgkmcnt(0)
	v_perm_b32 v16, v38, v37, s99
	ds_read_u16 v35, v34 offset:35208
	ds_read_u16 v36, v34 offset:36236
	ds_read_u16 v37, v34 offset:37264
	ds_read_u16 v38, v34 offset:39320
	ds_read_u16 v39, v34 offset:40348
	ds_read_u16 v40, v34 offset:38292
	ds_read_u16 v41, v34 offset:33152
	ds_read_u16 v42, v34 offset:34180
	s_waitcnt vmcnt(6)
	v_mfma_f32_16x16x32_bf16 v[16:19], v[16:19], v[0:3], 0
	s_waitcnt lgkmcnt(3)
	v_perm_b32 v39, v39, v38, s99
	s_waitcnt lgkmcnt(2)
	v_perm_b32 v38, v40, v37, s99
	v_perm_b32 v37, v36, v35, s99
	s_waitcnt lgkmcnt(0)
	v_perm_b32 v36, v42, v41, s99
	s_waitcnt vmcnt(5)
	s_nop 0
	v_mfma_f32_16x16x32_bf16 v[16:19], v[36:39], v[4:7], v[16:19]
	s_and_saveexec_b64 s[16:17], s[8:9]
	s_cbranch_execnz .LBB0_173
	s_or_b64 exec, exec, s[16:17]
	s_and_saveexec_b64 s[16:17], s[8:9]
	s_cbranch_execnz .LBB0_174

; DI unsigned pk2(float lo, float hi) { unsigned r; asm("v_cvt_pk_bf16_f32 %0, %1, %2" : "=v"(r) : "v"(lo), "v"(hi)); return r; }
; DI float bflo(unsigned u) { return __uint_as_float(u << 16); }
; DI float bfhi(unsigned u) { return __uint_as_float(u & 0xffff0000u); }
; DI float silu(float x) { return x * __builtin_amdgcn_rcpf(1.f + __expf(-x)); }
; DI void mix_gmlp(CP& p, int l, int ci, LAS unsigned char* lds) {
;     ...
; #pragma unroll
;         for (int ks = 0; ks < 4; ++ks) {
;           if (ks < nks) {
;             bf16x8 vf;
; #pragma unroll
;             for (int e = 0; e < 8; ++e) vf[e] = (short)vn[(32 * ks + 8 * fq + e) * VSTR + g * 128 + ct * 16 + fr];
;             acc = __builtin_amdgcn_mfma_f32_16x16x32_bf16(vf, wf[ks], acc, 0, 0, 0);
;           }
;         }
;         const int c0 = g * 128 + ct * 16 + 4 * fq;
;         if (i < nvalid) {
;           const u16* pr = proj + (size_t)(r0 + i) * NPROJ;
;           const u32x2 au = *(const u32x2*)(pr + C_AU + c0), ag = *(const u32x2*)(pr + C_AG + c0);
;           const float o0 = bflo(au.x) * (acc.x + bsv) * silu(bflo(ag.x)), o1 = bfhi(au.x) * (acc.y + bsv) * silu(bfhi(ag.x));
;           const float o2 = bflo(au.y) * (acc.z + bsv) * silu(bflo(ag.y)), o3 = bfhi(au.y) * (acc.w + bsv) * silu(bfhi(ag.y));
;           u32x2 o; o.x = pk2(o0, o1); o.y = pk2(o2, o3);
;           *(u32x2*)(y + (size_t)(r0 + i) * DM + c0) = o;
.LBB0_173:
	v_add_u32_e32 v35, 0x10200, v34
	v_add_u32_e32 v36, 0x10604, v34
	v_add_u32_e32 v37, 0x10a08, v34
	v_add_u32_e32 v38, 0x10e0c, v34
	v_add_u32_e32 v39, 0x11210, v34
	v_add_u32_e32 v40, 0x11614, v34
	v_add_u32_e32 v41, 0x11a18, v34
	v_add_u32_e32 v42, 0x11e1c, v34
	ds_read_u16 v37, v37
	ds_read_u16 v43, v38
	ds_read_u16 v38, v39
	ds_read_u16 v39, v41
	ds_read_u16 v41, v42
	ds_read_u16 v40, v40
	ds_read_u16 v35, v35
	ds_read_u16 v36, v36
	s_waitcnt lgkmcnt(6)
	v_perm_b32 v37, v43, v37, s99
	s_waitcnt lgkmcnt(3)
	v_perm_b32 v39, v41, v39, s99
	s_waitcnt lgkmcnt(2)
	v_perm_b32 v38, v40, v38, s99
	s_waitcnt lgkmcnt(0)
	v_perm_b32 v36, v36, v35, s99
	s_waitcnt vmcnt(4)
	s_nop 0
	v_mfma_f32_16x16x32_bf16 v[16:19], v[36:39], v[8:11], v[16:19]
	s_or_b64 exec, exec, s[16:17]
	s_and_saveexec_b64 s[16:17], s[8:9]
	s_cbranch_execz .LBB0_172
.LBB0_174:
	v_add_u32_e32 v35, 0x18280, v34
	v_add_u32_e32 v36, 0x18684, v34
	v_add_u32_e32 v37, 0x18a88, v34
	v_add_u32_e32 v38, 0x18e8c, v34
	v_add_u32_e32 v39, 0x19290, v34
	v_add_u32_e32 v40, 0x19694, v34
	v_add_u32_e32 v41, 0x19a98, v34
	v_add_u32_e32 v34, 0x19e9c, v34
	ds_read_u16 v42, v37
	ds_read_u16 v38, v38
	ds_read_u16 v39, v39
	ds_read_u16 v37, v41
	ds_read_u16 v34, v34
	ds_read_u16 v40, v40
	ds_read_u16 v41, v35
	ds_read_u16 v43, v36
	s_waitcnt lgkmcnt(6)
	v_perm_b32 v35, v38, v42, s99
	s_waitcnt lgkmcnt(3)
	v_perm_b32 v37, v34, v37, s99
	s_waitcnt lgkmcnt(2)
	v_perm_b32 v36, v40, v39, s99
	s_waitcnt lgkmcnt(0)
	v_perm_b32 v34, v43, v41, s99
	s_waitcnt vmcnt(3)
	s_nop 0
	v_mfma_f32_16x16x32_bf16 v[16:19], v[34:37], v[12:15], v[16:19]
	s_or_b64 exec, exec, s[16:17]
	s_and_saveexec_b64 s[16:17], s[10:11]
	s_cbranch_execz .LBB0_169
.LBB0_175:
	s_waitcnt vmcnt(2)
	s_nop 1
	v_add_f32_e32 v38, v33, v17
	v_add_f32_e32 v40, v33, v19
	v_add_f32_e32 v16, v33, v16
	v_add_f32_e32 v18, v33, v18
	s_waitcnt vmcnt(1)
	v_mov_b32_e32 v34, v48
	v_mov_b32_e32 v35, v49
	v_lshlrev_b32_e32 v43, 16, v34
	v_and_b32_e32 v45, 0xffff0000, v34
	v_lshlrev_b32_e32 v47, 16, v35
	v_and_b32_e32 v35, 0xffff0000, v35
	v_mul_f32_e32 v17, 0xbfb8aa3b, v43
	v_mul_f32_e32 v19, 0xbfb8aa3b, v45
	s_waitcnt vmcnt(0)
	v_mov_b32_e32 v36, v50
	v_mov_b32_e32 v37, v51
	v_lshlrev_b32_e32 v42, 16, v36
	v_and_b32_e32 v44, 0xffff0000, v36
	v_lshlrev_b32_e32 v46, 16, v37
	v_and_b32_e32 v34, 0xffff0000, v37
	v_mul_f32_e32 v36, 0xbfb8aa3b, v47
	v_mul_f32_e32 v37, 0xbfb8aa3b, v35
	v_exp_f32_e32 v17, v17
	v_exp_f32_e32 v19, v19
	v_exp_f32_e32 v36, v36
	v_exp_f32_e32 v37, v37
	v_add_f32_e32 v17, 1.0, v17
	v_add_f32_e32 v19, 1.0, v19
	v_add_f32_e32 v36, 1.0, v36
	v_add_f32_e32 v37, 1.0, v37
	v_rcp_f32_e32 v17, v17
	v_rcp_f32_e32 v39, v19
	v_rcp_f32_e32 v19, v36
	v_rcp_f32_e32 v41, v37
	v_pk_mul_f32 v[16:17], v[16:17], v[42:43]
	v_pk_mul_f32 v[36:37], v[38:39], v[44:45]
	v_pk_mul_f32 v[18:19], v[18:19], v[46:47]
	v_pk_mul_f32 v[34:35], v[40:41], v[34:35]
	v_mul_f32_e32 v16, v16, v17
	v_mul_f32_e32 v17, v36, v37
	v_mul_f32_e32 v18, v18, v19
	v_mul_f32_e32 v19, v34, v35
	v_cvt_pk_bf16_f32 v16, v16, v17
	v_cvt_pk_bf16_f32 v17, v18, v19
	global_store_dwordx2 v[30:31], v[16:17], off
	s_branch .LBB0_169

; DI void mix_gmlp(CP& p, int l, int ci, LAS unsigned char* lds) {
;     ...
;       for (int ct = 0; ct < 8; ++ct) {
;         f32x4 acc = {0.f, 0.f, 0.f, 0.f};
; #pragma unroll
;         for (int ks = 0; ks < 4; ++ks) {
;           if (ks < nks) {
;             bf16x8 vf;
; #pragma unroll
;             for (int e = 0; e < 8; ++e) vf[e] = (short)vn[(32 * ks + 8 * fq + e) * VSTR + g * 128 + ct * 16 + fr];
;             acc = __builtin_amdgcn_mfma_f32_16x16x32_bf16(vf, wf[ks], acc, 0, 0, 0);
;           }
;         }
.LBB0_178:
	global_load_dwordx2 v[48:49], v[28:29], off
	global_load_dwordx2 v[50:51], v[28:29], off offset:-2048
	v_add_u32_e32 v34, s4, v32
	ds_read_u16 v16, v34 offset:2568
	ds_read_u16 v17, v34 offset:3596
	ds_read_u16 v18, v34 offset:4624
	ds_read_u16 v19, v34 offset:6680
	ds_read_u16 v35, v34 offset:7708
	ds_read_u16 v36, v34 offset:5652
	ds_read_u16 v37, v34 offset:512
	ds_read_u16 v38, v34 offset:1540
	s_waitcnt lgkmcnt(6)
	v_perm_b32 v17, v17, v16, s99
	s_waitcnt lgkmcnt(3)
	v_perm_b32 v19, v35, v19, s99
	s_waitcnt lgkmcnt(2)
	v_perm_b32 v18, v36, v18, s99
	s_waitcnt lgkmcnt(0)
	v_perm_b32 v16, v38, v37, s99
	ds_read_u16 v35, v34 offset:35464
	ds_read_u16 v36, v34 offset:36492
	ds_read_u16 v37, v34 offset:37520
	ds_read_u16 v38, v34 offset:39576
	ds_read_u16 v39, v34 offset:40604
	ds_read_u16 v40, v34 offset:38548
	ds_read_u16 v41, v34 offset:33408
	ds_read_u16 v42, v34 offset:34436
	s_waitcnt vmcnt(6)
	v_mfma_f32_16x16x32_bf16 v[16:19], v[16:19], v[0:3], 0
	s_waitcnt lgkmcnt(3)
	v_perm_b32 v39, v39, v38, s99
	s_waitcnt lgkmcnt(2)
	v_perm_b32 v38, v40, v37, s99
	v_perm_b32 v37, v36, v35, s99
	s_waitcnt lgkmcnt(0)
	v_perm_b32 v36, v42, v41, s99
	s_waitcnt vmcnt(5)
	s_nop 0
	v_mfma_f32_16x16x32_bf16 v[16:19], v[36:39], v[4:7], v[16:19]
	s_and_saveexec_b64 s[16:17], s[8:9]
	s_cbranch_execnz .LBB0_181
	s_or_b64 exec, exec, s[16:17]
	s_and_saveexec_b64 s[16:17], s[8:9]
	s_cbranch_execnz .LBB0_182

; DI void mix_gmlp(CP& p, int l, int ci, LAS unsigned char* lds) {
;     ...
; #pragma unroll
;         for (int ks = 0; ks < 4; ++ks) {
;           if (ks < nks) {
;             bf16x8 vf;
; #pragma unroll
;             for (int e = 0; e < 8; ++e) vf[e] = (short)vn[(32 * ks + 8 * fq + e) * VSTR + g * 128 + ct * 16 + fr];
;             acc = __builtin_amdgcn_mfma_f32_16x16x32_bf16(vf, wf[ks], acc, 0, 0, 0);
;           }
;         }
.LBB0_181:
	v_add_u32_e32 v35, 0x10300, v34
	v_add_u32_e32 v36, 0x10704, v34
	v_add_u32_e32 v37, 0x10b08, v34
	v_add_u32_e32 v38, 0x10f0c, v34
	v_add_u32_e32 v39, 0x11310, v34
	v_add_u32_e32 v40, 0x11714, v34
	v_add_u32_e32 v41, 0x11b18, v34
	v_add_u32_e32 v42, 0x11f1c, v34
	ds_read_u16 v37, v37
	ds_read_u16 v43, v38
	ds_read_u16 v38, v39
	ds_read_u16 v39, v41
	ds_read_u16 v41, v42
	ds_read_u16 v40, v40
	ds_read_u16 v35, v35
	ds_read_u16 v36, v36
	s_waitcnt lgkmcnt(6)
	v_perm_b32 v37, v43, v37, s99
	s_waitcnt lgkmcnt(3)
	v_perm_b32 v39, v41, v39, s99
	s_waitcnt lgkmcnt(2)
	v_perm_b32 v38, v40, v38, s99
	s_waitcnt lgkmcnt(0)
	v_perm_b32 v36, v36, v35, s99
	s_waitcnt vmcnt(4)
	s_nop 0
	v_mfma_f32_16x16x32_bf16 v[16:19], v[36:39], v[8:11], v[16:19]
	s_or_b64 exec, exec, s[16:17]
	s_and_saveexec_b64 s[16:17], s[8:9]
	s_cbranch_execz .LBB0_180
.LBB0_182:
	v_add_u32_e32 v35, 0x18380, v34
	v_add_u32_e32 v36, 0x18784, v34
	v_add_u32_e32 v37, 0x18b88, v34
	v_add_u32_e32 v38, 0x18f8c, v34
	v_add_u32_e32 v39, 0x19390, v34
	v_add_u32_e32 v40, 0x19794, v34
	v_add_u32_e32 v41, 0x19b98, v34
	v_add_u32_e32 v34, 0x19f9c, v34
	ds_read_u16 v42, v37
	ds_read_u16 v38, v38
	ds_read_u16 v39, v39
	ds_read_u16 v37, v41
	ds_read_u16 v34, v34
	ds_read_u16 v40, v40
	ds_read_u16 v41, v35
	ds_read_u16 v43, v36
	s_waitcnt lgkmcnt(6)
	v_perm_b32 v35, v38, v42, s99
	s_waitcnt lgkmcnt(3)
	v_perm_b32 v37, v34, v37, s99
	s_waitcnt lgkmcnt(2)
	v_perm_b32 v36, v40, v39, s99
	s_waitcnt lgkmcnt(0)
	v_perm_b32 v34, v43, v41, s99
	s_waitcnt vmcnt(3)
	s_nop 0
	v_mfma_f32_16x16x32_bf16 v[16:19], v[34:37], v[12:15], v[16:19]
	s_or_b64 exec, exec, s[16:17]
	s_and_saveexec_b64 s[16:17], s[10:11]
	s_cbranch_execz .LBB0_177

; DI void mix_gmlp(CP& p, int l, int ci, LAS unsigned char* lds) {
;     ...
;       for (int ct = 0; ct < 8; ++ct) {
;         f32x4 acc = {0.f, 0.f, 0.f, 0.f};
; #pragma unroll
;         for (int ks = 0; ks < 4; ++ks) {
;           if (ks < nks) {
;             bf16x8 vf;
; #pragma unroll
;             for (int e = 0; e < 8; ++e) vf[e] = (short)vn[(32 * ks + 8 * fq + e) * VSTR + g * 128 + ct * 16 + fr];
;             acc = __builtin_amdgcn_mfma_f32_16x16x32_bf16(vf, wf[ks], acc, 0, 0, 0);
;           }
;         }
.LBB0_186:
	global_load_dwordx2 v[48:49], v[20:21], off
	global_load_dwordx2 v[50:51], v[20:21], off offset:-2048
	v_add_u32_e32 v24, s4, v32
	ds_read_u16 v16, v24 offset:2824
	ds_read_u16 v17, v24 offset:3852
	ds_read_u16 v18, v24 offset:4880
	ds_read_u16 v19, v24 offset:6936
	ds_read_u16 v25, v24 offset:7964
	ds_read_u16 v26, v24 offset:5908
	ds_read_u16 v27, v24 offset:768
	ds_read_u16 v29, v24 offset:1796
	s_waitcnt lgkmcnt(6)
	v_perm_b32 v17, v17, v16, s99
	s_waitcnt lgkmcnt(3)
	v_perm_b32 v19, v25, v19, s99
	s_waitcnt lgkmcnt(2)
	v_perm_b32 v18, v26, v18, s99
	s_waitcnt lgkmcnt(0)
	v_perm_b32 v16, v29, v27, s99
	ds_read_u16 v25, v24 offset:35720
	ds_read_u16 v26, v24 offset:36748
	ds_read_u16 v27, v24 offset:37776
	ds_read_u16 v29, v24 offset:39832
	ds_read_u16 v30, v24 offset:40860
	ds_read_u16 v31, v24 offset:38804
	s_waitcnt vmcnt(7)
	ds_read_u16 v33, v24 offset:33664
	ds_read_u16 v34, v24 offset:34692
	s_waitcnt lgkmcnt(6)
	v_perm_b32 v35, v26, v25, s99
	s_waitcnt lgkmcnt(3)
	v_perm_b32 v37, v30, v29, s99
	s_waitcnt lgkmcnt(2)
	v_perm_b32 v36, v31, v27, s99
	s_waitcnt vmcnt(6)
	v_mfma_f32_16x16x32_bf16 v[16:19], v[16:19], v[0:3], 0
	s_waitcnt lgkmcnt(0)
	v_perm_b32 v34, v34, v33, s99
	s_waitcnt vmcnt(5)
	s_nop 0
	v_mfma_f32_16x16x32_bf16 v[16:19], v[34:37], v[4:7], v[16:19]
	s_and_saveexec_b64 s[16:17], s[8:9]
	s_cbranch_execnz .LBB0_189
	s_or_b64 exec, exec, s[16:17]
	s_and_saveexec_b64 s[16:17], s[8:9]
	s_cbranch_execnz .LBB0_190

; DI unsigned pk2(float lo, float hi) { unsigned r; asm("v_cvt_pk_bf16_f32 %0, %1, %2" : "=v"(r) : "v"(lo), "v"(hi)); return r; }
; DI float bflo(unsigned u) { return __uint_as_float(u << 16); }
; DI float bfhi(unsigned u) { return __uint_as_float(u & 0xffff0000u); }
; DI float silu(float x) { return x * __builtin_amdgcn_rcpf(1.f + __expf(-x)); }
; DI void mix_gmlp(CP& p, int l, int ci, LAS unsigned char* lds) {
;     ...
; #pragma unroll
;         for (int ks = 0; ks < 4; ++ks) {
;           if (ks < nks) {
;             bf16x8 vf;
; #pragma unroll
;             for (int e = 0; e < 8; ++e) vf[e] = (short)vn[(32 * ks + 8 * fq + e) * VSTR + g * 128 + ct * 16 + fr];
;             acc = __builtin_amdgcn_mfma_f32_16x16x32_bf16(vf, wf[ks], acc, 0, 0, 0);
;           }
;         }
;         const int c0 = g * 128 + ct * 16 + 4 * fq;
;         if (i < nvalid) {
;           const u16* pr = proj + (size_t)(r0 + i) * NPROJ;
;           const u32x2 au = *(const u32x2*)(pr + C_AU + c0), ag = *(const u32x2*)(pr + C_AG + c0);
;           const float o0 = bflo(au.x) * (acc.x + bsv) * silu(bflo(ag.x)), o1 = bfhi(au.x) * (acc.y + bsv) * silu(bfhi(ag.x));
;           const float o2 = bflo(au.y) * (acc.z + bsv) * silu(bflo(ag.y)), o3 = bfhi(au.y) * (acc.w + bsv) * silu(bfhi(ag.y));
;           u32x2 o; o.x = pk2(o0, o1); o.y = pk2(o2, o3);
;           *(u32x2*)(y + (size_t)(r0 + i) * DM + c0) = o;
.LBB0_189:
	v_add_u32_e32 v25, 0x10400, v24
	v_add_u32_e32 v26, 0x10804, v24
	v_add_u32_e32 v27, 0x10c08, v24
	v_add_u32_e32 v29, 0x1100c, v24
	v_add_u32_e32 v30, 0x11410, v24
	v_add_u32_e32 v31, 0x11814, v24
	v_add_u32_e32 v33, 0x11c18, v24
	v_add_u32_e32 v34, 0x1201c, v24
	ds_read_u16 v27, v27
	ds_read_u16 v29, v29
	ds_read_u16 v30, v30
	ds_read_u16 v33, v33
	ds_read_u16 v34, v34
	ds_read_u16 v31, v31
	ds_read_u16 v25, v25
	ds_read_u16 v26, v26
	s_waitcnt lgkmcnt(6)
	v_perm_b32 v35, v29, v27, s99
	s_waitcnt lgkmcnt(3)
	v_perm_b32 v37, v34, v33, s99
	s_waitcnt lgkmcnt(2)
	v_perm_b32 v36, v31, v30, s99
	s_waitcnt lgkmcnt(0)
	v_perm_b32 v34, v26, v25, s99
	s_waitcnt vmcnt(4)
	s_nop 0
	v_mfma_f32_16x16x32_bf16 v[16:19], v[34:37], v[8:11], v[16:19]
	s_or_b64 exec, exec, s[16:17]
	s_and_saveexec_b64 s[16:17], s[8:9]
	s_cbranch_execz .LBB0_188
.LBB0_190:
	v_add_u32_e32 v25, 0x18480, v24
	v_add_u32_e32 v26, 0x18884, v24
	v_add_u32_e32 v27, 0x18c88, v24
	v_add_u32_e32 v29, 0x1908c, v24
	v_add_u32_e32 v30, 0x19490, v24
	v_add_u32_e32 v31, 0x19894, v24
	v_add_u32_e32 v33, 0x19c98, v24
	v_add_u32_e32 v24, 0x1a09c, v24
	ds_read_u16 v34, v27
	ds_read_u16 v29, v29
	ds_read_u16 v30, v30
	ds_read_u16 v27, v33
	ds_read_u16 v24, v24
	ds_read_u16 v31, v31
	ds_read_u16 v33, v25
	ds_read_u16 v35, v26
	s_waitcnt lgkmcnt(6)
	v_perm_b32 v25, v29, v34, s99
	s_waitcnt lgkmcnt(3)
	v_perm_b32 v27, v24, v27, s99
	s_waitcnt lgkmcnt(2)
	v_perm_b32 v26, v31, v30, s99
	s_waitcnt lgkmcnt(0)
	v_perm_b32 v24, v35, v33, s99
	s_waitcnt vmcnt(3)
	s_nop 0
	v_mfma_f32_16x16x32_bf16 v[16:19], v[24:27], v[12:15], v[16:19]
	s_or_b64 exec, exec, s[16:17]
	s_and_saveexec_b64 s[16:17], s[10:11]
	s_cbranch_execz .LBB0_185
.LBB0_191:
	s_waitcnt vmcnt(2)
	s_nop 1
	v_add_f32_e32 v30, v28, v17
	v_add_f32_e32 v34, v28, v19
	v_add_f32_e32 v16, v28, v16
	v_add_f32_e32 v18, v28, v18
	s_waitcnt vmcnt(1)
	v_mov_b32_e32 v24, v48
	v_mov_b32_e32 v25, v49
	v_lshlrev_b32_e32 v37, 16, v24
	v_and_b32_e32 v39, 0xffff0000, v24
	v_lshlrev_b32_e32 v41, 16, v25
	v_and_b32_e32 v25, 0xffff0000, v25
	v_mul_f32_e32 v17, 0xbfb8aa3b, v37
	v_mul_f32_e32 v19, 0xbfb8aa3b, v39
	s_waitcnt vmcnt(0)
	v_mov_b32_e32 v26, v50
	v_mov_b32_e32 v27, v51
	v_lshlrev_b32_e32 v36, 16, v26
	v_and_b32_e32 v38, 0xffff0000, v26
	v_lshlrev_b32_e32 v40, 16, v27
	v_and_b32_e32 v24, 0xffff0000, v27
	v_mul_f32_e32 v26, 0xbfb8aa3b, v41
	v_mul_f32_e32 v27, 0xbfb8aa3b, v25
	v_exp_f32_e32 v17, v17
	v_exp_f32_e32 v19, v19
	v_exp_f32_e32 v26, v26
	v_exp_f32_e32 v27, v27
	v_add_f32_e32 v17, 1.0, v17
	v_add_f32_e32 v19, 1.0, v19
	v_add_f32_e32 v26, 1.0, v26
	v_add_f32_e32 v27, 1.0, v27
	v_rcp_f32_e32 v17, v17
	v_rcp_f32_e32 v31, v19
	v_rcp_f32_e32 v19, v26
	v_rcp_f32_e32 v35, v27
	v_pk_mul_f32 v[16:17], v[16:17], v[36:37]
	v_pk_mul_f32 v[26:27], v[30:31], v[38:39]
	v_pk_mul_f32 v[18:19], v[18:19], v[40:41]
	v_pk_mul_f32 v[24:25], v[34:35], v[24:25]
	v_mul_f32_e32 v16, v16, v17
	v_mul_f32_e32 v17, v26, v27
	v_mul_f32_e32 v18, v18, v19
	v_mul_f32_e32 v19, v24, v25
	v_cvt_pk_bf16_f32 v16, v16, v17
	v_cvt_pk_bf16_f32 v17, v18, v19
	global_store_dwordx2 v[22:23], v[16:17], off
	s_branch .LBB0_185
